# per-unit accumulator zeroing with 64 v_mov_b64 (was 128 v_mov_b32); loop-end offset bumps as 32-bit adds
# baseline (speedup 1.0000x reference)
; #define PG8_STAGE(bufoff, gbase, voff) do { _Pragma("unroll") for (int _i = 0; _i < 2; ++_i) \
;         __builtin_amdgcn_global_load_lds((const unsigned*)((const char*)(gbase) + (voff)[_i]), (PG8_LAS unsigned*)(lds + (bufoff) + ldsw + _i * 8192), 16, 0, 0); } while (0)
; #define PG8_LDA(dst, b, h) do { _Pragma("unroll") for (int m = 0; m < 4; ++m) _Pragma("unroll") for (int k = 0; k < 2; ++k) dst[m][k] = *(const PG8_LAS bf16x8*)(lds + PG8_SA(b, h) + aoff + m * 2048 + k * 1024); } while (0)
; #define PG8_LDB(dst, b, h) do { _Pragma("unroll") for (int n = 0; n < 2; ++n) _Pragma("unroll") for (int k = 0; k < 2; ++k) dst[n][k] = *(const PG8_LAS bf16x8*)(lds + PG8_SB(b, h) + boff + n * 2048 + k * 1024); } while (0)
; #define PG8_MMA(ai, bj, At, Bt) do { __builtin_amdgcn_s_setprio(1); _Pragma("unroll") for (int m = 0; m < 4; ++m) _Pragma("unroll") for (int n = 0; n < 2; ++n) _Pragma("unroll") for (int k = 0; k < 2; ++k) \
;         acc[ai][bj][m][n] = __builtin_amdgcn_mfma_f32_16x16x32_bf16(Bt[n][k], At[m][k], acc[ai][bj][m][n], 0, 0, 0); __builtin_amdgcn_s_setprio(0); } while (0)
; #define PG8_WAIT_V(n) asm volatile("s_waitcnt vmcnt(" #n ")" ::: "memory")
; #define PG8_BAR __builtin_amdgcn_s_barrier()
; template <class Epi, class Sched, bool ALIGN_EPI = false, bool SP2 = false>
; __device__ __forceinline__ void gemm_phase(PG8_LAS unsigned char* lds, const Gemm g, const Sched& S, const Epi& E, const int tid_in) {
;     ...
;         for (int t = 0; t < nt; t += 2) {
;             const bool last = (t == nt - 2);
;             const char* a1 = cA + (size_t)(t + 1) * kstep;
;             const char* a2 = last ? nA : cA + (size_t)(t + 2) * kstep; const char* b2 = last ? nB : cB + (size_t)(t + 2) * kstep;
;             const char* a3 = a2 + kstep; const char* b3 = b2 + kstep;
;             if (last && has_next) S.a_ready(nxt);
;             if constexpr (SP2) {
;             PG8_LDB(B0, 0, 0); PG8_LDB(B1, 0, 1); PG8_SCHED; PG8_LDA(At, 0, 0); PG8_STAGE(PG8_SA(1, 1), a1 + hstep, voffA);
;             PG8_WAIT_V(8); PG8_WAIT_L(0); PG8_BAR; PG8_MMA(0, 0, At, B0); PG8_MMA(0, 1, At, B1); PG8_BAR; PG8_SCHED;
;             PG8_LDA(At, 0, 1); PG8_STAGE(PG8_SB(0, 0), b2, voffB); PG8_STAGE(PG8_SB(0, 1), b2 + hstep, voffB); PG8_STAGE(PG8_SA(0, 0), a2, voffA);
;             PG8_WAIT_V(8); PG8_WAIT_L(0); PG8_BAR; PG8_MMA(1, 0, At, B0); PG8_MMA(1, 1, At, B1); PG8_BAR; PG8_SCHED;
.LBB0_115:
	ds_read_b128 v[134:137], v248
	ds_read_b128 v[138:141], v248 offset:1024
	ds_read_b128 v[142:145], v248 offset:2048
	ds_read_b128 v[146:149], v248 offset:3072
	ds_read_b128 v[150:153], v249
	ds_read_b128 v[154:157], v249 offset:1024
	ds_read_b128 v[158:161], v249 offset:2048
	ds_read_b128 v[180:183], v249 offset:3072
	ds_read_b128 v[184:187], v179
	ds_read_b128 v[188:191], v179 offset:1024
	ds_read_b128 v[192:195], v179 offset:2048
	ds_read_b128 v[196:199], v179 offset:3072
	ds_read_b128 v[200:203], v179 offset:4096
	ds_read_b128 v[204:207], v179 offset:5120
	ds_read_b128 v[208:211], v179 offset:6144
	ds_read_b128 v[212:215], v179 offset:7168
	s_add_i32 m0, s60, 0xc000
	s_add_i32 s77, s52, 2
	s_add_u32 vcc_lo, s2, s10
	s_addc_u32 s53, s3, s11
	s_add_u32 s44, s50, s10
	s_addc_u32 s45, s51, s11
	s_cmp_eq_u32 s68, s52
	s_cselect_b32 s53, s49, s53
	s_cselect_b32 s52, s48, vcc_lo
	s_cselect_b32 vcc_hi, s43, s45
	s_cselect_b32 vcc_lo, s42, s44
	s_add_i32 s16, 0, 0x10000
	s_add_i32 s17, 0, 0x14000
	global_load_lds_dwordx4 v132, s[2:3]
	s_add_i32 m0, s60, 0xe000
	s_nop 0
	global_load_lds_dwordx4 v130, s[2:3]
	s_waitcnt vmcnt(8)
	s_waitcnt lgkmcnt(0)
	s_barrier
	s_setprio 1
	s_waitcnt lgkmcnt(0)
	v_mfma_f32_16x16x32_bf16 v[126:129], v[134:137], v[184:187], v[126:129]
	v_mfma_f32_16x16x32_bf16 v[122:125], v[142:145], v[184:187], v[122:125]
	v_mfma_f32_16x16x32_bf16 v[110:113], v[134:137], v[192:195], v[110:113]
	v_mfma_f32_16x16x32_bf16 v[106:109], v[142:145], v[192:195], v[106:109]
	v_mfma_f32_16x16x32_bf16 v[94:97], v[134:137], v[200:203], v[94:97]
	v_mfma_f32_16x16x32_bf16 v[90:93], v[142:145], v[200:203], v[90:93]
	v_mfma_f32_16x16x32_bf16 v[78:81], v[134:137], v[208:211], v[78:81]
	v_mfma_f32_16x16x32_bf16 v[74:77], v[142:145], v[208:211], v[74:77]
	v_mfma_f32_16x16x32_bf16 v[126:129], v[138:141], v[188:191], v[126:129]
	v_mfma_f32_16x16x32_bf16 v[122:125], v[146:149], v[188:191], v[122:125]
	v_mfma_f32_16x16x32_bf16 v[110:113], v[138:141], v[196:199], v[110:113]
	v_mfma_f32_16x16x32_bf16 v[106:109], v[146:149], v[196:199], v[106:109]
	v_mfma_f32_16x16x32_bf16 v[94:97], v[138:141], v[204:207], v[94:97]
	v_mfma_f32_16x16x32_bf16 v[90:93], v[146:149], v[204:207], v[90:93]
	v_mfma_f32_16x16x32_bf16 v[78:81], v[138:141], v[212:215], v[78:81]
	v_mfma_f32_16x16x32_bf16 v[74:77], v[146:149], v[212:215], v[74:77]
	s_setprio 0
	s_setprio 1
	v_mfma_f32_16x16x32_bf16 v[118:121], v[150:153], v[184:187], v[118:121]
	v_mfma_f32_16x16x32_bf16 v[114:117], v[158:161], v[184:187], v[114:117]
	v_mfma_f32_16x16x32_bf16 v[102:105], v[150:153], v[192:195], v[102:105]
	v_mfma_f32_16x16x32_bf16 v[98:101], v[158:161], v[192:195], v[98:101]
	v_mfma_f32_16x16x32_bf16 v[86:89], v[150:153], v[200:203], v[86:89]
	v_mfma_f32_16x16x32_bf16 v[82:85], v[158:161], v[200:203], v[82:85]
	v_mfma_f32_16x16x32_bf16 v[70:73], v[150:153], v[208:211], v[70:73]
	v_mfma_f32_16x16x32_bf16 v[66:69], v[158:161], v[208:211], v[66:69]
	v_mfma_f32_16x16x32_bf16 v[118:121], v[154:157], v[188:191], v[118:121]
	v_mfma_f32_16x16x32_bf16 v[114:117], v[180:183], v[188:191], v[114:117]
	v_mfma_f32_16x16x32_bf16 v[102:105], v[154:157], v[196:199], v[102:105]
	v_mfma_f32_16x16x32_bf16 v[98:101], v[180:183], v[196:199], v[98:101]
	v_mfma_f32_16x16x32_bf16 v[86:89], v[154:157], v[204:207], v[86:89]
	v_mfma_f32_16x16x32_bf16 v[82:85], v[180:183], v[204:207], v[82:85]
	v_mfma_f32_16x16x32_bf16 v[70:73], v[154:157], v[212:215], v[70:73]
	v_mfma_f32_16x16x32_bf16 v[66:69], v[180:183], v[212:215], v[66:69]
	s_setprio 0
	s_barrier
	s_add_i32 s16, s16, s59
	s_mov_b32 m0, s16
	ds_read_b128 v[184:187], v179 offset:16384
	ds_read_b128 v[188:191], v179 offset:17408
	ds_read_b128 v[192:195], v179 offset:18432
	ds_read_b128 v[196:199], v179 offset:19456
	ds_read_b128 v[200:203], v179 offset:20480
	ds_read_b128 v[204:207], v179 offset:21504
	ds_read_b128 v[208:211], v179 offset:22528
	ds_read_b128 v[212:215], v179 offset:23552
	global_load_lds_dwordx4 v164, vcc
	s_add_i32 m0, s16, 0x2000
	s_add_i32 s16, s17, s59
	global_load_lds_dwordx4 v168, vcc
	s_add_u32 s98, vcc_lo, 0x80
	s_addc_u32 s99, vcc_hi, 0
	s_add_u32 vcc_lo, vcc_lo, s82
	s_addc_u32 vcc_hi, vcc_hi, 0
	s_mov_b32 m0, s16
	s_add_u32 s100, s52, 0x80
	s_addc_u32 s101, s53, 0
	global_load_lds_dwordx4 v164, vcc
	s_add_i32 m0, s16, 0x2000
	s_nop 0
	global_load_lds_dwordx4 v168, vcc
	s_mov_b32 m0, s60
	s_nop 0
	global_load_lds_dwordx4 v162, s[52:53]
	s_mov_b32 m0, s61
	s_nop 0
	global_load_lds_dwordx4 v166, s[52:53]
	s_waitcnt vmcnt(8)
	s_waitcnt lgkmcnt(0)
	s_barrier
; #define PG8_STAGE(bufoff, gbase, voff) do { _Pragma("unroll") for (int _i = 0; _i < 2; ++_i) \
;         __builtin_amdgcn_global_load_lds((const unsigned*)((const char*)(gbase) + (voff)[_i]), (PG8_LAS unsigned*)(lds + (bufoff) + ldsw + _i * 8192), 16, 0, 0); } while (0)
; #define PG8_LDA(dst, b, h) do { _Pragma("unroll") for (int m = 0; m < 4; ++m) _Pragma("unroll") for (int k = 0; k < 2; ++k) dst[m][k] = *(const PG8_LAS bf16x8*)(lds + PG8_SA(b, h) + aoff + m * 2048 + k * 1024); } while (0)
; #define PG8_LDB(dst, b, h) do { _Pragma("unroll") for (int n = 0; n < 2; ++n) _Pragma("unroll") for (int k = 0; k < 2; ++k) dst[n][k] = *(const PG8_LAS bf16x8*)(lds + PG8_SB(b, h) + boff + n * 2048 + k * 1024); } while (0)
; #define PG8_MMA(ai, bj, At, Bt) do { __builtin_amdgcn_s_setprio(1); _Pragma("unroll") for (int m = 0; m < 4; ++m) _Pragma("unroll") for (int n = 0; n < 2; ++n) _Pragma("unroll") for (int k = 0; k < 2; ++k) \
;         acc[ai][bj][m][n] = __builtin_amdgcn_mfma_f32_16x16x32_bf16(Bt[n][k], At[m][k], acc[ai][bj][m][n], 0, 0, 0); __builtin_amdgcn_s_setprio(0); } while (0)
; #define PG8_WAIT_V(n) asm volatile("s_waitcnt vmcnt(" #n ")" ::: "memory")
; #define PG8_WAIT_L(n) asm volatile("s_waitcnt lgkmcnt(" #n ")" ::: "memory")
; #define PG8_BAR __builtin_amdgcn_s_barrier()
; #define PG8_SCHED __builtin_amdgcn_sched_barrier(0)
; template <class Epi, class Sched, bool ALIGN_EPI = false, bool SP2 = false>
; __device__ __forceinline__ void gemm_phase(PG8_LAS unsigned char* lds, const Gemm g, const Sched& S, const Epi& E, const int tid_in) {
;     ...
;             PG8_WAIT_V(8); PG8_WAIT_L(0); PG8_BAR; PG8_MMA(1, 0, At, B0); PG8_MMA(1, 1, At, B1); PG8_BAR; PG8_SCHED;
;             PG8_LDB(B0, 1, 0); PG8_LDB(B1, 1, 1); PG8_SCHED; PG8_LDA(At, 1, 0); PG8_STAGE(PG8_SA(0, 1), a2 + hstep, voffA);
;             PG8_WAIT_V(8); PG8_WAIT_L(0); PG8_BAR; PG8_MMA(0, 0, At, B0); PG8_MMA(0, 1, At, B1); PG8_BAR; PG8_SCHED;
	s_setprio 1
	s_waitcnt lgkmcnt(0)
	v_mfma_f32_16x16x32_bf16 v[62:65], v[134:137], v[184:187], v[62:65]
	v_mfma_f32_16x16x32_bf16 v[58:61], v[142:145], v[184:187], v[58:61]
	v_mfma_f32_16x16x32_bf16 v[46:49], v[134:137], v[192:195], v[46:49]
	v_mfma_f32_16x16x32_bf16 v[42:45], v[142:145], v[192:195], v[42:45]
	v_mfma_f32_16x16x32_bf16 v[30:33], v[134:137], v[200:203], v[30:33]
	v_mfma_f32_16x16x32_bf16 v[26:29], v[142:145], v[200:203], v[26:29]
	v_mfma_f32_16x16x32_bf16 v[14:17], v[134:137], v[208:211], v[14:17]
	v_mfma_f32_16x16x32_bf16 v[10:13], v[142:145], v[208:211], v[10:13]
	v_mfma_f32_16x16x32_bf16 v[62:65], v[138:141], v[188:191], v[62:65]
	v_mfma_f32_16x16x32_bf16 v[58:61], v[146:149], v[188:191], v[58:61]
	v_mfma_f32_16x16x32_bf16 v[46:49], v[138:141], v[196:199], v[46:49]
	v_mfma_f32_16x16x32_bf16 v[42:45], v[146:149], v[196:199], v[42:45]
	v_mfma_f32_16x16x32_bf16 v[30:33], v[138:141], v[204:207], v[30:33]
	v_mfma_f32_16x16x32_bf16 v[26:29], v[146:149], v[204:207], v[26:29]
	v_mfma_f32_16x16x32_bf16 v[14:17], v[138:141], v[212:215], v[14:17]
	v_mfma_f32_16x16x32_bf16 v[10:13], v[146:149], v[212:215], v[10:13]
	s_setprio 0
	s_setprio 1
	v_mfma_f32_16x16x32_bf16 v[54:57], v[150:153], v[184:187], v[54:57]
	v_mfma_f32_16x16x32_bf16 v[50:53], v[158:161], v[184:187], v[50:53]
	v_mfma_f32_16x16x32_bf16 v[38:41], v[150:153], v[192:195], v[38:41]
	v_mfma_f32_16x16x32_bf16 v[34:37], v[158:161], v[192:195], v[34:37]
	v_mfma_f32_16x16x32_bf16 v[22:25], v[150:153], v[200:203], v[22:25]
	v_mfma_f32_16x16x32_bf16 v[18:21], v[158:161], v[200:203], v[18:21]
	v_mfma_f32_16x16x32_bf16 v[6:9], v[150:153], v[208:211], v[6:9]
	v_mfma_f32_16x16x32_bf16 v[2:5], v[158:161], v[208:211], v[2:5]
	v_mfma_f32_16x16x32_bf16 v[54:57], v[154:157], v[188:191], v[54:57]
	v_mfma_f32_16x16x32_bf16 v[50:53], v[180:183], v[188:191], v[50:53]
	v_mfma_f32_16x16x32_bf16 v[38:41], v[154:157], v[196:199], v[38:41]
	v_mfma_f32_16x16x32_bf16 v[34:37], v[180:183], v[196:199], v[34:37]
	v_mfma_f32_16x16x32_bf16 v[22:25], v[154:157], v[204:207], v[22:25]
	v_mfma_f32_16x16x32_bf16 v[18:21], v[180:183], v[204:207], v[18:21]
	v_mfma_f32_16x16x32_bf16 v[6:9], v[154:157], v[212:215], v[6:9]
	v_mfma_f32_16x16x32_bf16 v[2:5], v[180:183], v[212:215], v[2:5]
	s_setprio 0
	s_barrier
	ds_read_b128 v[134:137], v250
	ds_read_b128 v[138:141], v250 offset:1024
	ds_read_b128 v[142:145], v250 offset:2048
	ds_read_b128 v[146:149], v250 offset:3072
	ds_read_b128 v[150:153], v251
	ds_read_b128 v[154:157], v251 offset:1024
	ds_read_b128 v[158:161], v251 offset:2048
	ds_read_b128 v[180:183], v251 offset:3072
	s_add_i32 s16, 0, 0x18000
	s_add_i32 s17, 0, 0x1c000
	s_add_u32 s52, s52, s82
	s_addc_u32 s53, s53, 0
	s_mov_b32 m0, s62
	ds_read_b128 v[184:187], v179 offset:32768
	ds_read_b128 v[188:191], v179 offset:33792
	ds_read_b128 v[192:195], v179 offset:34816
	ds_read_b128 v[196:199], v179 offset:35840
	ds_read_b128 v[200:203], v179 offset:36864
	ds_read_b128 v[204:207], v179 offset:37888
	ds_read_b128 v[208:211], v179 offset:38912
	ds_read_b128 v[212:215], v179 offset:39936
	global_load_lds_dwordx4 v162, s[52:53]
	s_mov_b32 m0, s63
	s_nop 0
	global_load_lds_dwordx4 v166, s[52:53]
	s_waitcnt vmcnt(8)
	s_waitcnt lgkmcnt(0)
	s_barrier
	s_setprio 1
	s_waitcnt lgkmcnt(0)
	v_mfma_f32_16x16x32_bf16 v[126:129], v[134:137], v[184:187], v[126:129]
	v_mfma_f32_16x16x32_bf16 v[122:125], v[142:145], v[184:187], v[122:125]
	v_mfma_f32_16x16x32_bf16 v[110:113], v[134:137], v[192:195], v[110:113]
	v_mfma_f32_16x16x32_bf16 v[106:109], v[142:145], v[192:195], v[106:109]
	v_mfma_f32_16x16x32_bf16 v[94:97], v[134:137], v[200:203], v[94:97]
	v_mfma_f32_16x16x32_bf16 v[90:93], v[142:145], v[200:203], v[90:93]
	v_mfma_f32_16x16x32_bf16 v[78:81], v[134:137], v[208:211], v[78:81]
	v_mfma_f32_16x16x32_bf16 v[74:77], v[142:145], v[208:211], v[74:77]
	v_mfma_f32_16x16x32_bf16 v[126:129], v[138:141], v[188:191], v[126:129]
	v_mfma_f32_16x16x32_bf16 v[122:125], v[146:149], v[188:191], v[122:125]
	v_mfma_f32_16x16x32_bf16 v[110:113], v[138:141], v[196:199], v[110:113]
	v_mfma_f32_16x16x32_bf16 v[106:109], v[146:149], v[196:199], v[106:109]
	v_mfma_f32_16x16x32_bf16 v[94:97], v[138:141], v[204:207], v[94:97]
	v_mfma_f32_16x16x32_bf16 v[90:93], v[146:149], v[204:207], v[90:93]
	v_mfma_f32_16x16x32_bf16 v[78:81], v[138:141], v[212:215], v[78:81]
	v_mfma_f32_16x16x32_bf16 v[74:77], v[146:149], v[212:215], v[74:77]
	s_setprio 0
	s_setprio 1
	v_mfma_f32_16x16x32_bf16 v[118:121], v[150:153], v[184:187], v[118:121]
	v_mfma_f32_16x16x32_bf16 v[114:117], v[158:161], v[184:187], v[114:117]
	v_mfma_f32_16x16x32_bf16 v[102:105], v[150:153], v[192:195], v[102:105]
	v_mfma_f32_16x16x32_bf16 v[98:101], v[158:161], v[192:195], v[98:101]
	v_mfma_f32_16x16x32_bf16 v[86:89], v[150:153], v[200:203], v[86:89]
	v_mfma_f32_16x16x32_bf16 v[82:85], v[158:161], v[200:203], v[82:85]
	v_mfma_f32_16x16x32_bf16 v[70:73], v[150:153], v[208:211], v[70:73]
	v_mfma_f32_16x16x32_bf16 v[66:69], v[158:161], v[208:211], v[66:69]
	v_mfma_f32_16x16x32_bf16 v[118:121], v[154:157], v[188:191], v[118:121]
	v_mfma_f32_16x16x32_bf16 v[114:117], v[180:183], v[188:191], v[114:117]
	v_mfma_f32_16x16x32_bf16 v[102:105], v[154:157], v[196:199], v[102:105]
	v_mfma_f32_16x16x32_bf16 v[98:101], v[180:183], v[196:199], v[98:101]
	v_mfma_f32_16x16x32_bf16 v[86:89], v[154:157], v[204:207], v[86:89]
	v_mfma_f32_16x16x32_bf16 v[82:85], v[180:183], v[204:207], v[82:85]
	v_mfma_f32_16x16x32_bf16 v[70:73], v[154:157], v[212:215], v[70:73]
	v_mfma_f32_16x16x32_bf16 v[66:69], v[180:183], v[212:215], v[66:69]
	s_setprio 0
	s_barrier
; #define PG8_STAGE(bufoff, gbase, voff) do { _Pragma("unroll") for (int _i = 0; _i < 2; ++_i) \
;         __builtin_amdgcn_global_load_lds((const unsigned*)((const char*)(gbase) + (voff)[_i]), (PG8_LAS unsigned*)(lds + (bufoff) + ldsw + _i * 8192), 16, 0, 0); } while (0)
; #define PG8_LDA(dst, b, h) do { _Pragma("unroll") for (int m = 0; m < 4; ++m) _Pragma("unroll") for (int k = 0; k < 2; ++k) dst[m][k] = *(const PG8_LAS bf16x8*)(lds + PG8_SA(b, h) + aoff + m * 2048 + k * 1024); } while (0)
; #define PG8_MMA(ai, bj, At, Bt) do { __builtin_amdgcn_s_setprio(1); _Pragma("unroll") for (int m = 0; m < 4; ++m) _Pragma("unroll") for (int n = 0; n < 2; ++n) _Pragma("unroll") for (int k = 0; k < 2; ++k) \
;         acc[ai][bj][m][n] = __builtin_amdgcn_mfma_f32_16x16x32_bf16(Bt[n][k], At[m][k], acc[ai][bj][m][n], 0, 0, 0); __builtin_amdgcn_s_setprio(0); } while (0)
; #define PG8_WAIT_V(n) asm volatile("s_waitcnt vmcnt(" #n ")" ::: "memory")
; #define PG8_WAIT_L(n) asm volatile("s_waitcnt lgkmcnt(" #n ")" ::: "memory")
; #define PG8_BAR __builtin_amdgcn_s_barrier()
; #define PG8_SCHED __builtin_amdgcn_sched_barrier(0)
; template <class Epi, class Sched, bool ALIGN_EPI = false, bool SP2 = false>
; __device__ __forceinline__ void gemm_phase(PG8_LAS unsigned char* lds, const Gemm g, const Sched& S, const Epi& E, const int tid_in) {
;     ...
;         for (int t = 0; t < nt; t += 2) {
;             const bool last = (t == nt - 2);
;             const char* a1 = cA + (size_t)(t + 1) * kstep;
;             const char* a2 = last ? nA : cA + (size_t)(t + 2) * kstep; const char* b2 = last ? nB : cB + (size_t)(t + 2) * kstep;
;     ...
;             PG8_LDA(At, 1, 1); PG8_STAGE(PG8_SB(1, 0), b3, voffB); PG8_STAGE(PG8_SB(1, 1), b3 + hstep, voffB); PG8_STAGE(PG8_SA(1, 0), a3, voffA);
;             PG8_WAIT_V(8); PG8_WAIT_L(0); PG8_BAR; PG8_MMA(1, 0, At, B0); PG8_MMA(1, 1, At, B1); PG8_BAR; PG8_SCHED;
	s_add_i32 s16, s16, s59
	s_mov_b32 m0, s16
	ds_read_b128 v[184:187], v179 offset:49152
	ds_read_b128 v[188:191], v179 offset:50176
	ds_read_b128 v[192:195], v179 offset:51200
	ds_read_b128 v[196:199], v179 offset:52224
	ds_read_b128 v[200:203], v179 offset:53248
	ds_read_b128 v[204:207], v179 offset:54272
	ds_read_b128 v[208:211], v179 offset:55296
	ds_read_b128 v[212:215], v179 offset:56320
	global_load_lds_dwordx4 v164, s[98:99]
	s_add_i32 m0, s16, 0x2000
	s_add_i32 s16, s17, s59
	global_load_lds_dwordx4 v168, s[98:99]
	s_add_u32 vcc_lo, vcc_lo, 0x80
	s_addc_u32 vcc_hi, vcc_hi, 0
	s_mov_b32 m0, s16
	s_nop 0
	global_load_lds_dwordx4 v164, vcc
	s_add_i32 m0, s16, 0x2000
	s_nop 0
	global_load_lds_dwordx4 v168, vcc
	s_mov_b32 m0, s66
	s_nop 0
	global_load_lds_dwordx4 v162, s[100:101]
	s_mov_b32 m0, s67
	s_nop 0
	global_load_lds_dwordx4 v166, s[100:101]
	s_waitcnt vmcnt(8)
	s_waitcnt lgkmcnt(0)
	s_barrier
	s_setprio 1
	s_waitcnt lgkmcnt(0)
	v_mfma_f32_16x16x32_bf16 v[62:65], v[134:137], v[184:187], v[62:65]
	v_mfma_f32_16x16x32_bf16 v[58:61], v[142:145], v[184:187], v[58:61]
	v_mfma_f32_16x16x32_bf16 v[46:49], v[134:137], v[192:195], v[46:49]
	v_mfma_f32_16x16x32_bf16 v[42:45], v[142:145], v[192:195], v[42:45]
	v_mfma_f32_16x16x32_bf16 v[30:33], v[134:137], v[200:203], v[30:33]
	v_mfma_f32_16x16x32_bf16 v[26:29], v[142:145], v[200:203], v[26:29]
	v_mfma_f32_16x16x32_bf16 v[14:17], v[134:137], v[208:211], v[14:17]
	v_mfma_f32_16x16x32_bf16 v[10:13], v[142:145], v[208:211], v[10:13]
	v_mfma_f32_16x16x32_bf16 v[62:65], v[138:141], v[188:191], v[62:65]
	v_mfma_f32_16x16x32_bf16 v[58:61], v[146:149], v[188:191], v[58:61]
	v_mfma_f32_16x16x32_bf16 v[46:49], v[138:141], v[196:199], v[46:49]
	v_mfma_f32_16x16x32_bf16 v[42:45], v[146:149], v[196:199], v[42:45]
	v_mfma_f32_16x16x32_bf16 v[30:33], v[138:141], v[204:207], v[30:33]
	v_mfma_f32_16x16x32_bf16 v[26:29], v[146:149], v[204:207], v[26:29]
	v_mfma_f32_16x16x32_bf16 v[14:17], v[138:141], v[212:215], v[14:17]
	v_mfma_f32_16x16x32_bf16 v[10:13], v[146:149], v[212:215], v[10:13]
	s_setprio 0
	s_setprio 1
	v_mfma_f32_16x16x32_bf16 v[54:57], v[150:153], v[184:187], v[54:57]
	v_mfma_f32_16x16x32_bf16 v[50:53], v[158:161], v[184:187], v[50:53]
	v_mfma_f32_16x16x32_bf16 v[38:41], v[150:153], v[192:195], v[38:41]
	v_mfma_f32_16x16x32_bf16 v[34:37], v[158:161], v[192:195], v[34:37]
	v_mfma_f32_16x16x32_bf16 v[22:25], v[150:153], v[200:203], v[22:25]
	v_mfma_f32_16x16x32_bf16 v[18:21], v[158:161], v[200:203], v[18:21]
	v_mfma_f32_16x16x32_bf16 v[6:9], v[150:153], v[208:211], v[6:9]
	v_mfma_f32_16x16x32_bf16 v[2:5], v[158:161], v[208:211], v[2:5]
	v_mfma_f32_16x16x32_bf16 v[54:57], v[154:157], v[188:191], v[54:57]
	v_mfma_f32_16x16x32_bf16 v[50:53], v[180:183], v[188:191], v[50:53]
	v_mfma_f32_16x16x32_bf16 v[38:41], v[154:157], v[196:199], v[38:41]
	v_mfma_f32_16x16x32_bf16 v[34:37], v[180:183], v[196:199], v[34:37]
	v_mfma_f32_16x16x32_bf16 v[22:25], v[154:157], v[204:207], v[22:25]
	v_mfma_f32_16x16x32_bf16 v[18:21], v[180:183], v[204:207], v[18:21]
	v_mfma_f32_16x16x32_bf16 v[6:9], v[154:157], v[212:215], v[6:9]
	v_mfma_f32_16x16x32_bf16 v[2:5], v[180:183], v[212:215], v[2:5]
	s_setprio 0
	s_barrier
	s_add_u32 s10, s10, 0x100
	s_addc_u32 s11, s11, 0
	v_add_u32_e32 v132, 0x100, v132
	v_add_u32_e32 v130, 0x100, v130
	s_cmp_ge_u32 s77, s65
	s_mov_b32 s52, s77
	s_cbranch_scc0 .LBB0_115
	s_and_b64 vcc, exec, s[46:47]
	s_cbranch_vccz .LBB0_118
	s_barrier

; template <class Epi, class Sched, bool ALIGN_EPI = false, bool SP2 = false>
; __device__ __forceinline__ void gemm_phase(PG8_LAS unsigned char* lds, const Gemm g, const Sched& S, const Epi& E, const int tid_in) {
;     ...
; #pragma unroll
;         for (int a = 0; a < 2; ++a)
; #pragma unroll
;             for (int b = 0; b < 2; ++b)
; #pragma unroll
;                 for (int m = 0; m < 4; ++m)
; #pragma unroll
;                     for (int n = 0; n < 2; ++n) acc[a][b][m][n] = (f32x4){0.f, 0.f, 0.f, 0.f};
;         cur = nxt; cA = nA; cB = nB; ++ui;
.LBB0_143:
	s_mov_b32 s28, s74
	s_mov_b32 s56, s75
	s_mov_b64 s[50:51], s[42:43]
	s_mov_b64 s[2:3], s[48:49]
	s_mov_b32 s73, s76
	v_mov_b64_e32 v[2:3], 0
	v_mov_b64_e32 v[4:5], 0
	v_mov_b64_e32 v[6:7], 0
	v_mov_b64_e32 v[8:9], 0
	v_mov_b64_e32 v[10:11], 0
	v_mov_b64_e32 v[12:13], 0
	v_mov_b64_e32 v[14:15], 0
	v_mov_b64_e32 v[16:17], 0
	v_mov_b64_e32 v[18:19], 0
	v_mov_b64_e32 v[20:21], 0
	v_mov_b64_e32 v[22:23], 0
	v_mov_b64_e32 v[24:25], 0
	v_mov_b64_e32 v[26:27], 0
	v_mov_b64_e32 v[28:29], 0
	v_mov_b64_e32 v[30:31], 0
	v_mov_b64_e32 v[32:33], 0
	v_mov_b64_e32 v[34:35], 0
	v_mov_b64_e32 v[36:37], 0
	v_mov_b64_e32 v[38:39], 0
	v_mov_b64_e32 v[40:41], 0
	v_mov_b64_e32 v[42:43], 0
	v_mov_b64_e32 v[44:45], 0
	v_mov_b64_e32 v[46:47], 0
	v_mov_b64_e32 v[48:49], 0
	v_mov_b64_e32 v[50:51], 0
	v_mov_b64_e32 v[52:53], 0
	v_mov_b64_e32 v[54:55], 0
	v_mov_b64_e32 v[56:57], 0
	v_mov_b64_e32 v[58:59], 0
	v_mov_b64_e32 v[60:61], 0
	v_mov_b64_e32 v[62:63], 0
	v_mov_b64_e32 v[64:65], 0
	v_mov_b64_e32 v[66:67], 0
	v_mov_b64_e32 v[68:69], 0
	v_mov_b64_e32 v[70:71], 0
	v_mov_b64_e32 v[72:73], 0
	v_mov_b64_e32 v[74:75], 0
	v_mov_b64_e32 v[76:77], 0
	v_mov_b64_e32 v[78:79], 0
	v_mov_b64_e32 v[80:81], 0
	v_mov_b64_e32 v[82:83], 0
	v_mov_b64_e32 v[84:85], 0
	v_mov_b64_e32 v[86:87], 0
	v_mov_b64_e32 v[88:89], 0
	v_mov_b64_e32 v[90:91], 0
	v_mov_b64_e32 v[92:93], 0
	v_mov_b64_e32 v[94:95], 0
	v_mov_b64_e32 v[96:97], 0
	v_mov_b64_e32 v[98:99], 0
	v_mov_b64_e32 v[100:101], 0
	v_mov_b64_e32 v[102:103], 0
	v_mov_b64_e32 v[104:105], 0
	v_mov_b64_e32 v[106:107], 0
	v_mov_b64_e32 v[108:109], 0
	v_mov_b64_e32 v[110:111], 0
	v_mov_b64_e32 v[112:113], 0
	v_mov_b64_e32 v[114:115], 0
	v_mov_b64_e32 v[116:117], 0
	v_mov_b64_e32 v[118:119], 0
	v_mov_b64_e32 v[120:121], 0
	v_mov_b64_e32 v[122:123], 0
	v_mov_b64_e32 v[124:125], 0
	v_mov_b64_e32 v[126:127], 0
	v_mov_b64_e32 v[128:129], 0
